# v35: composite of v33 + ssq tile-head hoist (phases 1,3,8) + NSA window-branch in-place PV accumulation
# baseline (speedup 1.0000x reference)
.LBB0_1457:
	s_mov_b32 s98, 0
	s_add_i32 s2, s14, -1
	s_and_b32 s14, s2, s14
	s_cmp_eq_u32 s14, 0
	s_cselect_b64 s[10:11], -1, 0
	s_cmp_lg_u32 s14, 0
	s_cselect_b64 s[12:13], -1, 0
	s_ff1_i32_b32 s17, s14
	s_and_b64 vcc, exec, s[10:11]
	s_cbranch_vccnz .LBB0_1459
	s_mul_i32 s76, s17, 0x38000
	s_waitcnt vmcnt(1)
	v_lshl_add_u64 v[16:17], s[76:77], 1, v[100:101]
	s_waitcnt vmcnt(0)
	v_add_co_u32_e32 v20, vcc, 0x1000, v16
	s_nop 1
	v_addc_co_u32_e32 v21, vcc, 0, v17, vcc
	global_load_dwordx4 v[16:19], v[20:21], off offset:2048
	s_nop 0
	global_load_dwordx4 v[20:23], v[20:21], off offset:2304

.LBB0_1462:
	s_mul_i32 s2, s16, 0x4800
	v_add_u32_e32 v199, s2, v109
	s_waitcnt vmcnt(1)
	ds_write_b128 v199, v[16:19]
	v_add_u32_e32 v199, s2, v110
	s_waitcnt vmcnt(0)
	ds_write_b16 v199, v20
	ds_write_b16_d16_hi v199, v20 offset:144
	ds_write_b16 v199, v21 offset:288
	ds_write_b16_d16_hi v199, v21 offset:432
	ds_write_b16 v199, v22 offset:576
	ds_write_b16_d16_hi v199, v22 offset:720
	ds_write_b16 v199, v23 offset:864
	ds_write_b16_d16_hi v199, v23 offset:1008
.LBB0_1463:
	s_waitcnt lgkmcnt(0)
	s_barrier
	s_andn2_b64 vcc, exec, s[10:11]
	s_cbranch_vccz .LBB0_1476
	s_mov_b32 s18, s17
	s_nop 0
	s_cmp_lg_u32 s98, 0
	s_cbranch_scc1 .LBB0_1457
	v_mov_b32_e32 v24, v68
	v_mov_b32_e32 v25, v69
	v_mov_b32_e32 v26, v70
	v_mov_b32_e32 v27, v71
	v_mov_b32_e32 v28, v72
	v_mov_b32_e32 v29, v73
	v_mov_b32_e32 v30, v74
	v_mov_b32_e32 v31, v75
	v_mov_b32_e32 v36, v60
	v_mov_b32_e32 v37, v61
	v_mov_b32_e32 v38, v62
	v_mov_b32_e32 v39, v63
	v_mov_b32_e32 v44, v56
	v_mov_b32_e32 v45, v57
	v_mov_b32_e32 v46, v58
	v_mov_b32_e32 v47, v59
	v_mov_b32_e32 v32, v84
	v_mov_b32_e32 v33, v85
	v_mov_b32_e32 v34, v86
	v_mov_b32_e32 v35, v87
	v_mov_b32_e32 v40, v80
	v_mov_b32_e32 v41, v81
	v_mov_b32_e32 v42, v82
	v_mov_b32_e32 v43, v83
	v_mov_b32_e32 v48, v76
	v_mov_b32_e32 v49, v77
	v_mov_b32_e32 v50, v78
	v_mov_b32_e32 v51, v79
	v_mov_b32_e32 v52, v64
	v_mov_b32_e32 v53, v65
	v_mov_b32_e32 v54, v66
	v_mov_b32_e32 v55, v67
	v_mov_b32_e32 v130, v108
	v_mov_b32_e32 v131, v132
	v_mov_b32_e32 v102, v104
	v_mov_b32_e32 v103, v105
	s_branch .LBB0_1457

.LBB0_1472:
	s_andn2_b64 vcc, exec, s[4:5]
	s_cbranch_vccnz .LBB0_1474
	ds_read_b128 v[56:59], v132
	ds_read_b128 v[60:63], v132 offset:64
	s_nop 3
	ds_read_b128 v[68:71], v132 offset:2304
	ds_read_b128 v[72:75], v132 offset:2368
	ds_read_b128 v[80:83], v132 offset:4608
	ds_read_b128 v[84:87], v132 offset:4672
	ds_read_b128 v[134:137], v132 offset:6912
	ds_read_b128 v[138:141], v132 offset:6976
	s_waitcnt lgkmcnt(7)
	v_mfma_f32_16x16x32_bf16 v[64:67], v[56:59], v[0:3], 0
	s_waitcnt lgkmcnt(5)
	v_mfma_f32_16x16x32_bf16 v[76:79], v[68:71], v[0:3], 0
	v_mfma_f32_16x16x32_bf16 v[64:67], v[60:63], v[4:7], v[64:67]
	s_waitcnt lgkmcnt(4)
	v_mfma_f32_16x16x32_bf16 v[76:79], v[72:75], v[4:7], v[76:79]
	v_mfma_f32_16x16x32_bf16 v[56:59], v[56:59], v[8:11], 0
	s_nop 4
	v_fma_f32 v66, v66, s86, v108
	v_fma_f32 v67, v67, s86, v108
	v_pk_fma_f32 v[104:105], v[64:65], s[86:87], v[108:109] op_sel_hi:[1,0,0]
	v_pk_fma_f32 v[78:79], v[78:79], s[86:87], v[108:109] op_sel_hi:[1,0,0]
	v_exp_f32_e32 v132, v66
	v_exp_f32_e32 v133, v67
	s_waitcnt lgkmcnt(3)
	v_mfma_f32_16x16x32_bf16 v[64:67], v[80:83], v[0:3], 0
	v_fma_f32 v142, v76, s86, v108
	v_fma_f32 v143, v77, s86, v108
	v_exp_f32_e32 v146, v78
	v_exp_f32_e32 v147, v79
	s_waitcnt lgkmcnt(1)
	v_mfma_f32_16x16x32_bf16 v[76:79], v[134:137], v[0:3], 0
	v_exp_f32_e32 v104, v104
	v_exp_f32_e32 v105, v105
	v_exp_f32_e32 v142, v142
	v_mfma_f32_16x16x32_bf16 v[64:67], v[84:87], v[4:7], v[64:67]
	v_exp_f32_e32 v143, v143
	v_pk_add_f32 v[148:149], v[104:105], 0 op_sel_hi:[1,0]
	v_pk_add_f32 v[144:145], v[132:133], 0 op_sel_hi:[1,0]
	s_waitcnt lgkmcnt(0)
	v_mfma_f32_16x16x32_bf16 v[76:79], v[138:141], v[4:7], v[76:79]
	v_add_f32_e64 v148, v148, v142
	v_add_f32_e64 v149, v149, v143
	s_nop 0
	v_pk_fma_f32 v[66:67], v[66:67], s[86:87], v[108:109] op_sel_hi:[1,0,0]
	v_pk_fma_f32 v[64:65], v[64:65], s[86:87], v[108:109] op_sel_hi:[1,0,0]
	v_exp_f32_e32 v150, v66
	v_exp_f32_e32 v151, v67
	v_exp_f32_e32 v152, v64
	v_exp_f32_e32 v153, v65
	v_pk_fma_f32 v[66:67], v[76:77], s[86:87], v[108:109] op_sel_hi:[1,0,0]
	v_mfma_f32_16x16x32_bf16 v[56:59], v[60:63], v[12:15], v[56:59]
	v_fma_f32 v64, v78, s86, v108
	v_fma_f32 v65, v79, s86, v108
	v_exp_f32_e32 v154, v66
	v_exp_f32_e32 v155, v67
	v_mfma_f32_16x16x32_bf16 v[60:63], v[68:71], v[8:11], 0
	v_exp_f32_e32 v156, v64
	v_exp_f32_e32 v157, v65
	v_pk_add_f32 v[144:145], v[144:145], v[146:147]
	v_pk_add_f32 v[68:69], v[148:149], v[152:153]
	v_pk_add_f32 v[144:145], v[144:145], v[150:151]
	v_mfma_f32_16x16x32_bf16 v[60:63], v[72:75], v[12:15], v[60:63]
	v_add_f32_e64 v68, v68, v154
	v_add_f32_e64 v69, v69, v155
	v_pk_fma_f32 v[58:59], v[58:59], s[86:87], v[106:107] op_sel_hi:[1,0,0]
	v_pk_fma_f32 v[56:57], v[56:57], s[86:87], v[106:107] op_sel_hi:[1,0,0]
	v_mfma_f32_16x16x32_bf16 v[64:67], v[80:83], v[8:11], 0
	v_add_f32_e64 v80, v144, v156
	v_add_f32_e64 v81, v145, v157
	v_add_f32_e32 v144, v68, v69
	v_cvt_pk_bf16_f32 v68, v104, v105
	v_exp_f32_e32 v82, v56
	v_exp_f32_e32 v83, v57
	v_exp_f32_e32 v104, v58
	v_exp_f32_e32 v105, v59
	ds_read2_b64 v[56:59], v107 offset1:4
	v_pk_fma_f32 v[62:63], v[62:63], s[86:87], v[106:107] op_sel_hi:[1,0,0]
	v_pk_fma_f32 v[60:61], v[60:61], s[86:87], v[106:107] op_sel_hi:[1,0,0]
	v_cvt_pk_bf16_f32 v69, v132, v133
	v_mfma_f32_16x16x32_bf16 v[72:75], v[134:137], v[8:11], 0
	v_exp_f32_e32 v132, v60
	v_exp_f32_e32 v133, v61
	v_exp_f32_e32 v134, v62
	v_exp_f32_e32 v135, v63
	v_mfma_f32_16x16x32_bf16 v[64:67], v[84:87], v[12:15], v[64:67]
	v_cvt_pk_bf16_f32 v70, v142, v143
	v_cvt_pk_bf16_f32 v71, v146, v147
	v_cvt_pk_bf16_f32 v60, v82, v83
	v_mfma_f32_16x16x32_bf16 v[72:75], v[138:141], v[12:15], v[72:75]
	v_cvt_pk_bf16_f32 v61, v104, v105
	v_cvt_pk_bf16_f32 v62, v132, v133
	v_cvt_pk_bf16_f32 v63, v134, v135
	v_add_u32_e32 v140, 0x1000, v107
	s_waitcnt lgkmcnt(0)
	v_mfma_f32_16x16x32_bf16 v[52:55], v[56:59], v[68:71], v[52:55]
	v_add_u32_e32 v108, 0x800, v107
	v_add_u32_e32 v141, 0x1800, v107
	ds_read2_b64 v[76:79], v108 offset0:32 offset1:36
	v_mfma_f32_16x16x32_bf16 v[44:47], v[56:59], v[60:63], v[44:47]
	ds_read2_b64 v[56:59], v140 offset0:64 offset1:68
	v_pk_fma_f32 v[136:137], v[66:67], s[86:87], v[106:107] op_sel_hi:[1,0,0]
	v_pk_fma_f32 v[138:139], v[64:65], s[86:87], v[106:107] op_sel_hi:[1,0,0]
	ds_read2_b64 v[64:67], v141 offset0:96 offset1:100
	s_waitcnt lgkmcnt(1)
	v_mfma_f32_16x16x32_bf16 v[40:43], v[56:59], v[68:71], v[40:43]
	v_fma_f32 v74, v74, s86, v106
	v_fma_f32 v75, v75, s86, v106
	v_pk_fma_f32 v[72:73], v[72:73], s[86:87], v[106:107] op_sel_hi:[1,0,0]
	v_exp_f32_e32 v138, v138
	v_mfma_f32_16x16x32_bf16 v[28:31], v[56:59], v[60:63], v[28:31]
	ds_read2_b64 v[56:59], v107 offset0:8 offset1:12
	v_exp_f32_e32 v139, v139
	v_exp_f32_e32 v136, v136
	v_mfma_f32_16x16x32_bf16 v[36:39], v[76:79], v[60:63], v[36:39]
	v_exp_f32_e32 v137, v137
	v_exp_f32_e32 v72, v72
	v_exp_f32_e32 v73, v73
	s_waitcnt lgkmcnt(1)
	v_mfma_f32_16x16x32_bf16 v[24:27], v[64:67], v[60:63], v[24:27]
	ds_read2_b64 v[60:63], v108 offset0:40 offset1:44
	v_exp_f32_e32 v74, v74
	v_exp_f32_e32 v75, v75
	v_mfma_f32_16x16x32_bf16 v[48:51], v[76:79], v[68:71], v[48:51]
	v_cvt_pk_bf16_f32 v84, v152, v153
	v_cvt_pk_bf16_f32 v85, v150, v151
	v_cvt_pk_bf16_f32 v86, v154, v155
	v_cvt_pk_bf16_f32 v87, v156, v157
	v_mfma_f32_16x16x32_bf16 v[32:35], v[64:67], v[68:71], v[32:35]
	v_cvt_pk_bf16_f32 v68, v138, v139
	v_cvt_pk_bf16_f32 v69, v136, v137
	v_cvt_pk_bf16_f32 v70, v72, v73
	v_cvt_pk_bf16_f32 v71, v74, v75
	s_waitcnt lgkmcnt(1)
	v_mfma_f32_16x16x32_bf16 v[52:55], v[56:59], v[84:87], v[52:55]
	v_mfma_f32_16x16x32_bf16 v[44:47], v[56:59], v[68:71], v[44:47]
	v_add_f32_e64 v200, v104, 0
	v_add_f32_e64 v201, v105, 0
	v_add_f32_e32 v202, v80, v81
	ds_read2_b64 v[204:207], v140 offset0:72 offset1:76
	s_waitcnt lgkmcnt(1)
	v_mfma_f32_16x16x32_bf16 v[48:51], v[60:63], v[84:87], v[48:51]
	v_mfma_f32_16x16x32_bf16 v[36:39], v[60:63], v[68:71], v[36:39]
	v_add_f32_e64 v208, v82, 0
	v_add_f32_e64 v209, v83, 0
	v_pk_add_f32 v[210:211], v[200:201], v[134:135]
	v_pk_add_f32 v[208:209], v[208:209], v[132:133]
	ds_read2_b64 v[212:215], v141 offset0:104 offset1:108
	v_pk_add_f32 v[210:211], v[210:211], v[136:137]
	v_pk_add_f32 v[208:209], v[208:209], v[138:139]
	s_waitcnt lgkmcnt(1)
	v_mfma_f32_16x16x32_bf16 v[40:43], v[204:207], v[84:87], v[40:43]
	v_add_f32_e64 v216, v210, v74
	v_add_f32_e64 v217, v211, v75
	v_pk_add_f32 v[218:219], v[208:209], v[72:73]
	v_mfma_f32_16x16x32_bf16 v[28:31], v[204:207], v[68:71], v[28:31]
	v_pk_mov_b32 v[208:209], v[218:219], v[216:217] op_sel:[1,0]
	v_mov_b32_e32 v219, v217
	s_nop 0
	v_pk_add_f32 v[220:221], v[208:209], v[218:219]
	s_waitcnt lgkmcnt(0)
	v_mfma_f32_16x16x32_bf16 v[32:35], v[212:215], v[84:87], v[32:35]
	v_mov_b32_e32 v145, v220
	v_mov_b32_e32 v203, v221
	v_pk_add_f32 v[222:223], v[144:145], v[202:203]
	v_mfma_f32_16x16x32_bf16 v[24:27], v[212:215], v[68:71], v[24:27]
	v_add_f32_e64 v102, v102, v222
	v_add_f32_e64 v103, v103, v223
	s_mov_b32 s98, 1

amdhsa.kernels:
  - .agpr_count:     0
    .args:
      - .offset:         0
        .size:           352
        .value_kind:     by_value
      - .offset:         352
        .size:           4
        .value_kind:     by_value
      - .offset:         356
        .size:           4
        .value_kind:     by_value
      - .offset:         360
        .size:           4
        .value_kind:     hidden_block_count_x
      - .offset:         364
        .size:           4
        .value_kind:     hidden_block_count_y
      - .offset:         368
        .size:           4
        .value_kind:     hidden_block_count_z
      - .offset:         372
        .size:           2
        .value_kind:     hidden_group_size_x
      - .offset:         374
        .size:           2
        .value_kind:     hidden_group_size_y
      - .offset:         376
        .size:           2
        .value_kind:     hidden_group_size_z
      - .offset:         378
        .size:           2
        .value_kind:     hidden_remainder_x
      - .offset:         380
        .size:           2
        .value_kind:     hidden_remainder_y
      - .offset:         382
        .size:           2
        .value_kind:     hidden_remainder_z
      - .offset:         400
        .size:           8
        .value_kind:     hidden_global_offset_x
      - .offset:         408
        .size:           8
        .value_kind:     hidden_global_offset_y
      - .offset:         416
        .size:           8
        .value_kind:     hidden_global_offset_z
      - .offset:         424
        .size:           2
        .value_kind:     hidden_grid_dims
      - .offset:         448
        .size:           8
        .value_kind:     hidden_multigrid_sync_arg
      - .offset:         480
        .size:           4
        .value_kind:     hidden_dynamic_lds_size
    .group_segment_fixed_size: 0
    .kernarg_segment_align: 8
    .kernarg_segment_size: 616
    .language:       OpenCL C
    .language_version:
      - 2
      - 0
    .max_flat_workgroup_size: 512
    .name:           _Z4mega1Pii
    .private_segment_fixed_size: 0
    .sgpr_count:     106
    .sgpr_spill_count: 85
    .symbol:         _Z4mega1Pii.kd
    .uniform_work_group_size: 1
    .uses_dynamic_stack: false
    .vgpr_count:     256
    .vgpr_spill_count: 0
    .wavefront_size: 64
